# speedup vs baseline: 1.0232x; 1.0054x over previous
; #define SCHED __builtin_amdgcn_sched_barrier(0)
; __device__ __forceinline__ float silu_f(float g) {
;   return g * __builtin_amdgcn_rcpf(1.0f + __builtin_amdgcn_exp2f(-1.4426950408889634f * g));
; }
; template <int EPI, bool HS = false>
; __device__ __forceinline__ void gemm_phase(const Params& p, const GemmCfg& g, char* shm, const int wave_s) {
;     ...
;     } else if constexpr (EPI == EPI_SWIGLU) {
;       u16* ot = g.o16 + (size_t)orow0 * DFF + pn * 128;
;       const unsigned tb = (unsigned)((wr * 64 + fq * 4) * DFF + wc * 16 + fr);
; #pragma unroll
;       for (int ai = 0; ai < 2; ++ai)
; #pragma unroll
;         for (int m = 0; m < 4; ++m) {
;           const f32x4 r4 = *(const f32x4*)(rsw + ai * 128 + m * 16);
; #pragma unroll
;           for (int j = 0; j < 4; ++j)
; #pragma unroll
;             for (int bj = 0; bj < 2; ++bj) {
;               float gv = r4[j] * acc[ai][bj][m][0][j] + swv[bj][0], uv = r4[j] * acc[ai][bj][m][1][j] + swv[bj][1];
;               ot[tb + (ai * 128 + m * 16 + j) * DFF + bj * 64] = f2bf(silu_f(gv) * uv);
;             }
;           SCHED;
;         }
.LBB0_853:
	s_mov_b32 s5, -1
	v_mbcnt_lo_u32_b32 v0, s5, 0
	v_mbcnt_hi_u32_b32 v0, s5, v0
	s_mul_hi_i32 s3, s4, 0x1600
	s_mulk_i32 s4, 0x1600
	s_add_u32 s4, s90, s4
	s_addc_u32 s5, s91, s3
	s_lshl_b32 s2, s2, 7
	s_ashr_i32 s3, s2, 31
	s_lshl_b64 s[2:3], s[2:3], 1
	s_add_u32 s2, s4, s2
	s_addc_u32 s3, s5, s3
	v_and_b32_e32 v130, 15, v0
	v_lshrrev_b32_e32 v131, 4, v0
	v_lshrrev_b32_e32 v132, 2, v0
	v_and_b32_e32 v133, 3, v0
	s_andn2_b32 s4, s82, 3
	s_lshl_b32 s4, s4, 6
	v_lshl_add_u32 v142, v131, 4, s9
	v_add_u32_e32 v142, s4, v142
	ds_read_b128 v[146:149], v142
	ds_read_b128 v[150:153], v142 offset:64
	ds_read_b128 v[154:157], v142 offset:128
	ds_read_b128 v[158:161], v142 offset:192
	ds_read_b128 v[162:165], v142 offset:512
	ds_read_b128 v[166:169], v142 offset:576
	ds_read_b128 v[170:173], v142 offset:640
	ds_read_b128 v[174:177], v142 offset:704
	s_mul_i32 s4, s4, 0x580
	v_mul_u32_u24_e32 v145, 0x1600, v132
	v_add_u32_e32 v145, s4, v145
	s_and_b32 s5, s82, 3
	s_lshl_b32 s5, s5, 6
	v_lshl_add_u32 v145, v133, 4, v145
	v_add_u32_e32 v145, s5, v145
	s_lshl_b32 s5, s82, 10
	s_add_i32 s5, s5, 0x20800
	v_lshlrev_b32_e32 v143, 8, v131
	v_lshl_add_u32 v143, v130, 2, v143
	v_add_u32_e32 v143, s5, v143
	v_lshl_add_u32 v144, v0, 4, s5
	s_mov_b32 s20, 0xbfb8aa3b
	s_mov_b32 s21, 0xbfb8aa3b
	s_mov_b32 s22, 1.0
	s_mov_b32 s23, 1.0
	s_waitcnt lgkmcnt(0)
	v_pk_fma_f32 v[126:127], v[126:127], v[146:147], v[140:141] op_sel_hi:[1,1,0]
	v_pk_fma_f32 v[94:95], v[94:95], v[146:147], v[138:139] op_sel_hi:[1,1,0]
	v_pk_mul_f32 v[194:195], v[126:127], s[20:21]
	v_pk_mul_f32 v[196:197], v[94:95], s[20:21]
	v_exp_f32_e32 v194, v194
	v_exp_f32_e32 v195, v195
	v_exp_f32_e32 v196, v196
	v_exp_f32_e32 v197, v197
	v_pk_fma_f32 v[122:123], v[122:123], v[146:147], v[140:141] op_sel:[0,0,1] op_sel_hi:[1,1,1]
	v_pk_fma_f32 v[90:91], v[90:91], v[146:147], v[138:139] op_sel:[0,0,1] op_sel_hi:[1,1,1]
	v_pk_add_f32 v[194:195], v[194:195], s[22:23]
	v_pk_add_f32 v[196:197], v[196:197], s[22:23]
	v_rcp_f32_e32 v194, v194
	v_rcp_f32_e32 v195, v195
	v_rcp_f32_e32 v196, v196
	v_rcp_f32_e32 v197, v197
	v_pk_mul_f32 v[126:127], v[126:127], v[194:195]
	v_pk_mul_f32 v[94:95], v[94:95], v[196:197]
	v_pk_mul_f32 v[126:127], v[122:123], v[126:127]
	v_pk_mul_f32 v[94:95], v[90:91], v[94:95]
	v_cvt_pk_bf16_f32 v190, v126, v94
	v_cvt_pk_bf16_f32 v191, v127, v95
	v_pk_fma_f32 v[128:129], v[128:129], v[148:149], v[140:141] op_sel_hi:[1,1,0]
	v_pk_fma_f32 v[96:97], v[96:97], v[148:149], v[138:139] op_sel_hi:[1,1,0]
	v_pk_mul_f32 v[194:195], v[128:129], s[20:21]
	v_pk_mul_f32 v[196:197], v[96:97], s[20:21]
	v_exp_f32_e32 v194, v194
	v_exp_f32_e32 v195, v195
	v_exp_f32_e32 v196, v196
	v_exp_f32_e32 v197, v197
	v_pk_fma_f32 v[124:125], v[124:125], v[148:149], v[140:141] op_sel:[0,0,1] op_sel_hi:[1,1,1]
	v_pk_fma_f32 v[92:93], v[92:93], v[148:149], v[138:139] op_sel:[0,0,1] op_sel_hi:[1,1,1]
	v_pk_add_f32 v[194:195], v[194:195], s[22:23]
	v_pk_add_f32 v[196:197], v[196:197], s[22:23]
	v_rcp_f32_e32 v194, v194
	v_rcp_f32_e32 v195, v195
	v_rcp_f32_e32 v196, v196
	v_rcp_f32_e32 v197, v197
	v_pk_mul_f32 v[128:129], v[128:129], v[194:195]
	v_pk_mul_f32 v[96:97], v[96:97], v[196:197]
	v_pk_mul_f32 v[128:129], v[124:125], v[128:129]
	v_pk_mul_f32 v[96:97], v[92:93], v[96:97]
	v_cvt_pk_bf16_f32 v192, v128, v96
	v_cvt_pk_bf16_f32 v193, v129, v97
	s_waitcnt lgkmcnt(0)
	ds_write_b32 v143, v190
	ds_write_b32 v143, v191 offset:64
	ds_write_b32 v143, v192 offset:128
	ds_write_b32 v143, v193 offset:192
	ds_read_b128 v[180:183], v144
	v_pk_fma_f32 v[118:119], v[118:119], v[150:151], v[140:141] op_sel_hi:[1,1,0]
	v_pk_fma_f32 v[86:87], v[86:87], v[150:151], v[138:139] op_sel_hi:[1,1,0]
	v_pk_mul_f32 v[194:195], v[118:119], s[20:21]
	v_pk_mul_f32 v[196:197], v[86:87], s[20:21]
	v_exp_f32_e32 v194, v194
	v_exp_f32_e32 v195, v195
	v_exp_f32_e32 v196, v196
	v_exp_f32_e32 v197, v197
	v_pk_fma_f32 v[114:115], v[114:115], v[150:151], v[140:141] op_sel:[0,0,1] op_sel_hi:[1,1,1]
	v_pk_fma_f32 v[82:83], v[82:83], v[150:151], v[138:139] op_sel:[0,0,1] op_sel_hi:[1,1,1]
	v_pk_add_f32 v[194:195], v[194:195], s[22:23]
	v_pk_add_f32 v[196:197], v[196:197], s[22:23]
	v_rcp_f32_e32 v194, v194
	v_rcp_f32_e32 v195, v195
	v_rcp_f32_e32 v196, v196
	v_rcp_f32_e32 v197, v197
	v_pk_mul_f32 v[118:119], v[118:119], v[194:195]
	v_pk_mul_f32 v[86:87], v[86:87], v[196:197]
	v_pk_mul_f32 v[118:119], v[114:115], v[118:119]
	v_pk_mul_f32 v[86:87], v[82:83], v[86:87]
	v_cvt_pk_bf16_f32 v190, v118, v86
	v_cvt_pk_bf16_f32 v191, v119, v87
	v_pk_fma_f32 v[120:121], v[120:121], v[152:153], v[140:141] op_sel_hi:[1,1,0]
	v_pk_fma_f32 v[88:89], v[88:89], v[152:153], v[138:139] op_sel_hi:[1,1,0]
	v_pk_mul_f32 v[194:195], v[120:121], s[20:21]
	v_pk_mul_f32 v[196:197], v[88:89], s[20:21]
	v_exp_f32_e32 v194, v194
	v_exp_f32_e32 v195, v195
	v_exp_f32_e32 v196, v196
	v_exp_f32_e32 v197, v197
	v_pk_fma_f32 v[116:117], v[116:117], v[152:153], v[140:141] op_sel:[0,0,1] op_sel_hi:[1,1,1]
	v_pk_fma_f32 v[84:85], v[84:85], v[152:153], v[138:139] op_sel:[0,0,1] op_sel_hi:[1,1,1]
	v_pk_add_f32 v[194:195], v[194:195], s[22:23]
	v_pk_add_f32 v[196:197], v[196:197], s[22:23]
	v_rcp_f32_e32 v194, v194
	v_rcp_f32_e32 v195, v195
	v_rcp_f32_e32 v196, v196
	v_rcp_f32_e32 v197, v197
	v_pk_mul_f32 v[120:121], v[120:121], v[194:195]
	v_pk_mul_f32 v[88:89], v[88:89], v[196:197]
	v_pk_mul_f32 v[120:121], v[116:117], v[120:121]
	v_pk_mul_f32 v[88:89], v[84:85], v[88:89]
	v_cvt_pk_bf16_f32 v192, v120, v88
	v_cvt_pk_bf16_f32 v193, v121, v89
	s_waitcnt lgkmcnt(0)
; #define SCHED __builtin_amdgcn_sched_barrier(0)
; __device__ __forceinline__ float silu_f(float g) {
;   return g * __builtin_amdgcn_rcpf(1.0f + __builtin_amdgcn_exp2f(-1.4426950408889634f * g));
; }
; template <int EPI, bool HS = false>
; __device__ __forceinline__ void gemm_phase(const Params& p, const GemmCfg& g, char* shm, const int wave_s) {
;     ...
;     } else if constexpr (EPI == EPI_SWIGLU) {
;       u16* ot = g.o16 + (size_t)orow0 * DFF + pn * 128;
;       const unsigned tb = (unsigned)((wr * 64 + fq * 4) * DFF + wc * 16 + fr);
; #pragma unroll
;       for (int ai = 0; ai < 2; ++ai)
; #pragma unroll
;         for (int m = 0; m < 4; ++m) {
;           const f32x4 r4 = *(const f32x4*)(rsw + ai * 128 + m * 16);
; #pragma unroll
;           for (int j = 0; j < 4; ++j)
; #pragma unroll
;             for (int bj = 0; bj < 2; ++bj) {
;               float gv = r4[j] * acc[ai][bj][m][0][j] + swv[bj][0], uv = r4[j] * acc[ai][bj][m][1][j] + swv[bj][1];
;               ot[tb + (ai * 128 + m * 16 + j) * DFF + bj * 64] = f2bf(silu_f(gv) * uv);
;             }
;           SCHED;
;         }
	global_store_dwordx4 v145, v[180:183], s[2:3]
	s_add_u32 s2, s2, 0x16000
	s_addc_u32 s3, s3, 0
	ds_write_b32 v143, v190
	ds_write_b32 v143, v191 offset:64
	ds_write_b32 v143, v192 offset:128
	ds_write_b32 v143, v193 offset:192
	ds_read_b128 v[184:187], v144
	v_pk_fma_f32 v[110:111], v[110:111], v[154:155], v[140:141] op_sel_hi:[1,1,0]
	v_pk_fma_f32 v[78:79], v[78:79], v[154:155], v[138:139] op_sel_hi:[1,1,0]
	v_pk_mul_f32 v[194:195], v[110:111], s[20:21]
	v_pk_mul_f32 v[196:197], v[78:79], s[20:21]
	v_exp_f32_e32 v194, v194
	v_exp_f32_e32 v195, v195
	v_exp_f32_e32 v196, v196
	v_exp_f32_e32 v197, v197
	v_pk_fma_f32 v[106:107], v[106:107], v[154:155], v[140:141] op_sel:[0,0,1] op_sel_hi:[1,1,1]
	v_pk_fma_f32 v[74:75], v[74:75], v[154:155], v[138:139] op_sel:[0,0,1] op_sel_hi:[1,1,1]
	v_pk_add_f32 v[194:195], v[194:195], s[22:23]
	v_pk_add_f32 v[196:197], v[196:197], s[22:23]
	v_rcp_f32_e32 v194, v194
	v_rcp_f32_e32 v195, v195
	v_rcp_f32_e32 v196, v196
	v_rcp_f32_e32 v197, v197
	v_pk_mul_f32 v[110:111], v[110:111], v[194:195]
	v_pk_mul_f32 v[78:79], v[78:79], v[196:197]
	v_pk_mul_f32 v[110:111], v[106:107], v[110:111]
	v_pk_mul_f32 v[78:79], v[74:75], v[78:79]
	v_cvt_pk_bf16_f32 v190, v110, v78
	v_cvt_pk_bf16_f32 v191, v111, v79
	v_pk_fma_f32 v[112:113], v[112:113], v[156:157], v[140:141] op_sel_hi:[1,1,0]
	v_pk_fma_f32 v[80:81], v[80:81], v[156:157], v[138:139] op_sel_hi:[1,1,0]
	v_pk_mul_f32 v[194:195], v[112:113], s[20:21]
	v_pk_mul_f32 v[196:197], v[80:81], s[20:21]
	v_exp_f32_e32 v194, v194
	v_exp_f32_e32 v195, v195
	v_exp_f32_e32 v196, v196
	v_exp_f32_e32 v197, v197
	v_pk_fma_f32 v[108:109], v[108:109], v[156:157], v[140:141] op_sel:[0,0,1] op_sel_hi:[1,1,1]
	v_pk_fma_f32 v[76:77], v[76:77], v[156:157], v[138:139] op_sel:[0,0,1] op_sel_hi:[1,1,1]
	v_pk_add_f32 v[194:195], v[194:195], s[22:23]
	v_pk_add_f32 v[196:197], v[196:197], s[22:23]
	v_rcp_f32_e32 v194, v194
	v_rcp_f32_e32 v195, v195
	v_rcp_f32_e32 v196, v196
	v_rcp_f32_e32 v197, v197
	v_pk_mul_f32 v[112:113], v[112:113], v[194:195]
	v_pk_mul_f32 v[80:81], v[80:81], v[196:197]
	v_pk_mul_f32 v[112:113], v[108:109], v[112:113]
	v_pk_mul_f32 v[80:81], v[76:77], v[80:81]
	v_cvt_pk_bf16_f32 v192, v112, v80
	v_cvt_pk_bf16_f32 v193, v113, v81
	s_waitcnt lgkmcnt(0)
	global_store_dwordx4 v145, v[184:187], s[2:3]
	s_add_u32 s2, s2, 0x16000
	s_addc_u32 s3, s3, 0
	ds_write_b32 v143, v190
	ds_write_b32 v143, v191 offset:64
	ds_write_b32 v143, v192 offset:128
	ds_write_b32 v143, v193 offset:192
	ds_read_b128 v[180:183], v144
	v_pk_fma_f32 v[102:103], v[102:103], v[158:159], v[140:141] op_sel_hi:[1,1,0]
	v_pk_fma_f32 v[70:71], v[70:71], v[158:159], v[138:139] op_sel_hi:[1,1,0]
	v_pk_mul_f32 v[194:195], v[102:103], s[20:21]
	v_pk_mul_f32 v[196:197], v[70:71], s[20:21]
	v_exp_f32_e32 v194, v194
	v_exp_f32_e32 v195, v195
	v_exp_f32_e32 v196, v196
	v_exp_f32_e32 v197, v197
	v_pk_fma_f32 v[98:99], v[98:99], v[158:159], v[140:141] op_sel:[0,0,1] op_sel_hi:[1,1,1]
	v_pk_fma_f32 v[66:67], v[66:67], v[158:159], v[138:139] op_sel:[0,0,1] op_sel_hi:[1,1,1]
	v_pk_add_f32 v[194:195], v[194:195], s[22:23]
	v_pk_add_f32 v[196:197], v[196:197], s[22:23]
	v_rcp_f32_e32 v194, v194
	v_rcp_f32_e32 v195, v195
	v_rcp_f32_e32 v196, v196
	v_rcp_f32_e32 v197, v197
	v_pk_mul_f32 v[102:103], v[102:103], v[194:195]
	v_pk_mul_f32 v[70:71], v[70:71], v[196:197]
	v_pk_mul_f32 v[102:103], v[98:99], v[102:103]
	v_pk_mul_f32 v[70:71], v[66:67], v[70:71]
	v_cvt_pk_bf16_f32 v190, v102, v70
	v_cvt_pk_bf16_f32 v191, v103, v71
	v_pk_fma_f32 v[104:105], v[104:105], v[160:161], v[140:141] op_sel_hi:[1,1,0]
	v_pk_fma_f32 v[72:73], v[72:73], v[160:161], v[138:139] op_sel_hi:[1,1,0]
	v_pk_mul_f32 v[194:195], v[104:105], s[20:21]
	v_pk_mul_f32 v[196:197], v[72:73], s[20:21]
	v_exp_f32_e32 v194, v194
	v_exp_f32_e32 v195, v195
	v_exp_f32_e32 v196, v196
	v_exp_f32_e32 v197, v197
	v_pk_fma_f32 v[100:101], v[100:101], v[160:161], v[140:141] op_sel:[0,0,1] op_sel_hi:[1,1,1]
	v_pk_fma_f32 v[68:69], v[68:69], v[160:161], v[138:139] op_sel:[0,0,1] op_sel_hi:[1,1,1]
	v_pk_add_f32 v[194:195], v[194:195], s[22:23]
	v_pk_add_f32 v[196:197], v[196:197], s[22:23]
	v_rcp_f32_e32 v194, v194
	v_rcp_f32_e32 v195, v195
	v_rcp_f32_e32 v196, v196
	v_rcp_f32_e32 v197, v197
	v_pk_mul_f32 v[104:105], v[104:105], v[194:195]
	v_pk_mul_f32 v[72:73], v[72:73], v[196:197]
	v_pk_mul_f32 v[104:105], v[100:101], v[104:105]
	v_pk_mul_f32 v[72:73], v[68:69], v[72:73]
	v_cvt_pk_bf16_f32 v192, v104, v72
	v_cvt_pk_bf16_f32 v193, v105, v73
	s_waitcnt lgkmcnt(0)
	global_store_dwordx4 v145, v[180:183], s[2:3]
	s_add_u32 s2, s2, 0x16000
	s_addc_u32 s3, s3, 0
	ds_write_b32 v143, v190
	ds_write_b32 v143, v191 offset:64
	ds_write_b32 v143, v192 offset:128
	ds_write_b32 v143, v193 offset:192
	ds_read_b128 v[184:187], v144
	v_pk_fma_f32 v[62:63], v[62:63], v[162:163], v[140:141] op_sel_hi:[1,1,0]
	v_pk_fma_f32 v[30:31], v[30:31], v[162:163], v[138:139] op_sel_hi:[1,1,0]
	v_pk_mul_f32 v[194:195], v[62:63], s[20:21]
	v_pk_mul_f32 v[196:197], v[30:31], s[20:21]
	v_exp_f32_e32 v194, v194
	v_exp_f32_e32 v195, v195
	v_exp_f32_e32 v196, v196
	v_exp_f32_e32 v197, v197
	v_pk_fma_f32 v[58:59], v[58:59], v[162:163], v[140:141] op_sel:[0,0,1] op_sel_hi:[1,1,1]
	v_pk_fma_f32 v[26:27], v[26:27], v[162:163], v[138:139] op_sel:[0,0,1] op_sel_hi:[1,1,1]
	v_pk_add_f32 v[194:195], v[194:195], s[22:23]
	v_pk_add_f32 v[196:197], v[196:197], s[22:23]
	v_rcp_f32_e32 v194, v194
	v_rcp_f32_e32 v195, v195
	v_rcp_f32_e32 v196, v196
	v_rcp_f32_e32 v197, v197
	v_pk_mul_f32 v[62:63], v[62:63], v[194:195]
	v_pk_mul_f32 v[30:31], v[30:31], v[196:197]
	v_pk_mul_f32 v[62:63], v[58:59], v[62:63]
	v_pk_mul_f32 v[30:31], v[26:27], v[30:31]
	v_cvt_pk_bf16_f32 v190, v62, v30
	v_cvt_pk_bf16_f32 v191, v63, v31
	v_pk_fma_f32 v[64:65], v[64:65], v[164:165], v[140:141] op_sel_hi:[1,1,0]
	v_pk_fma_f32 v[32:33], v[32:33], v[164:165], v[138:139] op_sel_hi:[1,1,0]
	v_pk_mul_f32 v[194:195], v[64:65], s[20:21]
	v_pk_mul_f32 v[196:197], v[32:33], s[20:21]
	v_exp_f32_e32 v194, v194
	v_exp_f32_e32 v195, v195
	v_exp_f32_e32 v196, v196
	v_exp_f32_e32 v197, v197
	v_pk_fma_f32 v[60:61], v[60:61], v[164:165], v[140:141] op_sel:[0,0,1] op_sel_hi:[1,1,1]
	v_pk_fma_f32 v[28:29], v[28:29], v[164:165], v[138:139] op_sel:[0,0,1] op_sel_hi:[1,1,1]
	v_pk_add_f32 v[194:195], v[194:195], s[22:23]
	v_pk_add_f32 v[196:197], v[196:197], s[22:23]
	v_rcp_f32_e32 v194, v194
	v_rcp_f32_e32 v195, v195
	v_rcp_f32_e32 v196, v196
	v_rcp_f32_e32 v197, v197
	v_pk_mul_f32 v[64:65], v[64:65], v[194:195]
	v_pk_mul_f32 v[32:33], v[32:33], v[196:197]
	v_pk_mul_f32 v[64:65], v[60:61], v[64:65]
	v_pk_mul_f32 v[32:33], v[28:29], v[32:33]
	v_cvt_pk_bf16_f32 v192, v64, v32
	v_cvt_pk_bf16_f32 v193, v65, v33
	s_waitcnt lgkmcnt(0)
; #define SCHED __builtin_amdgcn_sched_barrier(0)
; __device__ __forceinline__ float silu_f(float g) {
;   return g * __builtin_amdgcn_rcpf(1.0f + __builtin_amdgcn_exp2f(-1.4426950408889634f * g));
; }
; template <int EPI, bool HS = false>
; __device__ __forceinline__ void gemm_phase(const Params& p, const GemmCfg& g, char* shm, const int wave_s) {
;     ...
;     } else if constexpr (EPI == EPI_SWIGLU) {
;       u16* ot = g.o16 + (size_t)orow0 * DFF + pn * 128;
;       const unsigned tb = (unsigned)((wr * 64 + fq * 4) * DFF + wc * 16 + fr);
; #pragma unroll
;       for (int ai = 0; ai < 2; ++ai)
; #pragma unroll
;         for (int m = 0; m < 4; ++m) {
;           const f32x4 r4 = *(const f32x4*)(rsw + ai * 128 + m * 16);
; #pragma unroll
;           for (int j = 0; j < 4; ++j)
; #pragma unroll
;             for (int bj = 0; bj < 2; ++bj) {
;               float gv = r4[j] * acc[ai][bj][m][0][j] + swv[bj][0], uv = r4[j] * acc[ai][bj][m][1][j] + swv[bj][1];
;               ot[tb + (ai * 128 + m * 16 + j) * DFF + bj * 64] = f2bf(silu_f(gv) * uv);
;             }
;           SCHED;
;         }
	global_store_dwordx4 v145, v[184:187], s[2:3]
	s_add_u32 s2, s2, 0x6e000
	s_addc_u32 s3, s3, 0
	ds_write_b32 v143, v190
	ds_write_b32 v143, v191 offset:64
	ds_write_b32 v143, v192 offset:128
	ds_write_b32 v143, v193 offset:192
	ds_read_b128 v[180:183], v144
	v_pk_fma_f32 v[54:55], v[54:55], v[166:167], v[140:141] op_sel_hi:[1,1,0]
	v_pk_fma_f32 v[22:23], v[22:23], v[166:167], v[138:139] op_sel_hi:[1,1,0]
	v_pk_mul_f32 v[194:195], v[54:55], s[20:21]
	v_pk_mul_f32 v[196:197], v[22:23], s[20:21]
	v_exp_f32_e32 v194, v194
	v_exp_f32_e32 v195, v195
	v_exp_f32_e32 v196, v196
	v_exp_f32_e32 v197, v197
	v_pk_fma_f32 v[50:51], v[50:51], v[166:167], v[140:141] op_sel:[0,0,1] op_sel_hi:[1,1,1]
	v_pk_fma_f32 v[18:19], v[18:19], v[166:167], v[138:139] op_sel:[0,0,1] op_sel_hi:[1,1,1]
	v_pk_add_f32 v[194:195], v[194:195], s[22:23]
	v_pk_add_f32 v[196:197], v[196:197], s[22:23]
	v_rcp_f32_e32 v194, v194
	v_rcp_f32_e32 v195, v195
	v_rcp_f32_e32 v196, v196
	v_rcp_f32_e32 v197, v197
	v_pk_mul_f32 v[54:55], v[54:55], v[194:195]
	v_pk_mul_f32 v[22:23], v[22:23], v[196:197]
	v_pk_mul_f32 v[54:55], v[50:51], v[54:55]
	v_pk_mul_f32 v[22:23], v[18:19], v[22:23]
	v_cvt_pk_bf16_f32 v190, v54, v22
	v_cvt_pk_bf16_f32 v191, v55, v23
	v_pk_fma_f32 v[56:57], v[56:57], v[168:169], v[140:141] op_sel_hi:[1,1,0]
	v_pk_fma_f32 v[24:25], v[24:25], v[168:169], v[138:139] op_sel_hi:[1,1,0]
	v_pk_mul_f32 v[194:195], v[56:57], s[20:21]
	v_pk_mul_f32 v[196:197], v[24:25], s[20:21]
	v_exp_f32_e32 v194, v194
	v_exp_f32_e32 v195, v195
	v_exp_f32_e32 v196, v196
	v_exp_f32_e32 v197, v197
	v_pk_fma_f32 v[52:53], v[52:53], v[168:169], v[140:141] op_sel:[0,0,1] op_sel_hi:[1,1,1]
	v_pk_fma_f32 v[20:21], v[20:21], v[168:169], v[138:139] op_sel:[0,0,1] op_sel_hi:[1,1,1]
	v_pk_add_f32 v[194:195], v[194:195], s[22:23]
	v_pk_add_f32 v[196:197], v[196:197], s[22:23]
	v_rcp_f32_e32 v194, v194
	v_rcp_f32_e32 v195, v195
	v_rcp_f32_e32 v196, v196
	v_rcp_f32_e32 v197, v197
	v_pk_mul_f32 v[56:57], v[56:57], v[194:195]
	v_pk_mul_f32 v[24:25], v[24:25], v[196:197]
	v_pk_mul_f32 v[56:57], v[52:53], v[56:57]
	v_pk_mul_f32 v[24:25], v[20:21], v[24:25]
	v_cvt_pk_bf16_f32 v192, v56, v24
	v_cvt_pk_bf16_f32 v193, v57, v25
	s_waitcnt lgkmcnt(0)
	global_store_dwordx4 v145, v[180:183], s[2:3]
	s_add_u32 s2, s2, 0x16000
	s_addc_u32 s3, s3, 0
	ds_write_b32 v143, v190
	ds_write_b32 v143, v191 offset:64
	ds_write_b32 v143, v192 offset:128
	ds_write_b32 v143, v193 offset:192
	ds_read_b128 v[184:187], v144
	v_pk_fma_f32 v[46:47], v[46:47], v[170:171], v[140:141] op_sel_hi:[1,1,0]
	v_pk_fma_f32 v[14:15], v[14:15], v[170:171], v[138:139] op_sel_hi:[1,1,0]
	v_pk_mul_f32 v[194:195], v[46:47], s[20:21]
	v_pk_mul_f32 v[196:197], v[14:15], s[20:21]
	v_exp_f32_e32 v194, v194
	v_exp_f32_e32 v195, v195
	v_exp_f32_e32 v196, v196
	v_exp_f32_e32 v197, v197
	v_pk_fma_f32 v[42:43], v[42:43], v[170:171], v[140:141] op_sel:[0,0,1] op_sel_hi:[1,1,1]
	v_pk_fma_f32 v[10:11], v[10:11], v[170:171], v[138:139] op_sel:[0,0,1] op_sel_hi:[1,1,1]
	v_pk_add_f32 v[194:195], v[194:195], s[22:23]
	v_pk_add_f32 v[196:197], v[196:197], s[22:23]
	v_rcp_f32_e32 v194, v194
	v_rcp_f32_e32 v195, v195
	v_rcp_f32_e32 v196, v196
	v_rcp_f32_e32 v197, v197
	v_pk_mul_f32 v[46:47], v[46:47], v[194:195]
	v_pk_mul_f32 v[14:15], v[14:15], v[196:197]
	v_pk_mul_f32 v[46:47], v[42:43], v[46:47]
	v_pk_mul_f32 v[14:15], v[10:11], v[14:15]
	v_cvt_pk_bf16_f32 v190, v46, v14
	v_cvt_pk_bf16_f32 v191, v47, v15
	v_pk_fma_f32 v[48:49], v[48:49], v[172:173], v[140:141] op_sel_hi:[1,1,0]
	v_pk_fma_f32 v[16:17], v[16:17], v[172:173], v[138:139] op_sel_hi:[1,1,0]
	v_pk_mul_f32 v[194:195], v[48:49], s[20:21]
	v_pk_mul_f32 v[196:197], v[16:17], s[20:21]
	v_exp_f32_e32 v194, v194
	v_exp_f32_e32 v195, v195
	v_exp_f32_e32 v196, v196
	v_exp_f32_e32 v197, v197
	v_pk_fma_f32 v[44:45], v[44:45], v[172:173], v[140:141] op_sel:[0,0,1] op_sel_hi:[1,1,1]
	v_pk_fma_f32 v[12:13], v[12:13], v[172:173], v[138:139] op_sel:[0,0,1] op_sel_hi:[1,1,1]
	v_pk_add_f32 v[194:195], v[194:195], s[22:23]
	v_pk_add_f32 v[196:197], v[196:197], s[22:23]
	v_rcp_f32_e32 v194, v194
	v_rcp_f32_e32 v195, v195
	v_rcp_f32_e32 v196, v196
	v_rcp_f32_e32 v197, v197
	v_pk_mul_f32 v[48:49], v[48:49], v[194:195]
	v_pk_mul_f32 v[16:17], v[16:17], v[196:197]
	v_pk_mul_f32 v[48:49], v[44:45], v[48:49]
	v_pk_mul_f32 v[16:17], v[12:13], v[16:17]
	v_cvt_pk_bf16_f32 v192, v48, v16
	v_cvt_pk_bf16_f32 v193, v49, v17
	s_waitcnt lgkmcnt(0)
	global_store_dwordx4 v145, v[184:187], s[2:3]
	s_add_u32 s2, s2, 0x16000
	s_addc_u32 s3, s3, 0
	ds_write_b32 v143, v190
	ds_write_b32 v143, v191 offset:64
	ds_write_b32 v143, v192 offset:128
	ds_write_b32 v143, v193 offset:192
	ds_read_b128 v[180:183], v144
	v_pk_fma_f32 v[38:39], v[38:39], v[174:175], v[140:141] op_sel_hi:[1,1,0]
	v_pk_fma_f32 v[6:7], v[6:7], v[174:175], v[138:139] op_sel_hi:[1,1,0]
	v_pk_mul_f32 v[194:195], v[38:39], s[20:21]
	v_pk_mul_f32 v[196:197], v[6:7], s[20:21]
	v_exp_f32_e32 v194, v194
	v_exp_f32_e32 v195, v195
	v_exp_f32_e32 v196, v196
	v_exp_f32_e32 v197, v197
	v_pk_fma_f32 v[34:35], v[34:35], v[174:175], v[140:141] op_sel:[0,0,1] op_sel_hi:[1,1,1]
	v_pk_fma_f32 v[2:3], v[2:3], v[174:175], v[138:139] op_sel:[0,0,1] op_sel_hi:[1,1,1]
	v_pk_add_f32 v[194:195], v[194:195], s[22:23]
	v_pk_add_f32 v[196:197], v[196:197], s[22:23]
	v_rcp_f32_e32 v194, v194
	v_rcp_f32_e32 v195, v195
	v_rcp_f32_e32 v196, v196
	v_rcp_f32_e32 v197, v197
	v_pk_mul_f32 v[38:39], v[38:39], v[194:195]
	v_pk_mul_f32 v[6:7], v[6:7], v[196:197]
	v_pk_mul_f32 v[38:39], v[34:35], v[38:39]
	v_pk_mul_f32 v[6:7], v[2:3], v[6:7]
	v_cvt_pk_bf16_f32 v190, v38, v6
	v_cvt_pk_bf16_f32 v191, v39, v7
	v_pk_fma_f32 v[40:41], v[40:41], v[176:177], v[140:141] op_sel_hi:[1,1,0]
	v_pk_fma_f32 v[8:9], v[8:9], v[176:177], v[138:139] op_sel_hi:[1,1,0]
	v_pk_mul_f32 v[194:195], v[40:41], s[20:21]
	v_pk_mul_f32 v[196:197], v[8:9], s[20:21]
	v_exp_f32_e32 v194, v194
	v_exp_f32_e32 v195, v195
	v_exp_f32_e32 v196, v196
	v_exp_f32_e32 v197, v197
	v_pk_fma_f32 v[36:37], v[36:37], v[176:177], v[140:141] op_sel:[0,0,1] op_sel_hi:[1,1,1]
	v_pk_fma_f32 v[4:5], v[4:5], v[176:177], v[138:139] op_sel:[0,0,1] op_sel_hi:[1,1,1]
	v_pk_add_f32 v[194:195], v[194:195], s[22:23]
	v_pk_add_f32 v[196:197], v[196:197], s[22:23]
	v_rcp_f32_e32 v194, v194
	v_rcp_f32_e32 v195, v195
	v_rcp_f32_e32 v196, v196
	v_rcp_f32_e32 v197, v197
	v_pk_mul_f32 v[40:41], v[40:41], v[194:195]
	v_pk_mul_f32 v[8:9], v[8:9], v[196:197]
	v_pk_mul_f32 v[40:41], v[36:37], v[40:41]
	v_pk_mul_f32 v[8:9], v[4:5], v[8:9]
	v_cvt_pk_bf16_f32 v192, v40, v8
	v_cvt_pk_bf16_f32 v193, v41, v9
	s_waitcnt lgkmcnt(0)
	global_store_dwordx4 v145, v[180:183], s[2:3]
	s_add_u32 s2, s2, 0x16000
	s_addc_u32 s3, s3, 0
	ds_write_b32 v143, v190
	ds_write_b32 v143, v191 offset:64
	ds_write_b32 v143, v192 offset:128
	ds_write_b32 v143, v193 offset:192
	ds_read_b128 v[184:187], v144
	s_waitcnt lgkmcnt(0)
	global_store_dwordx4 v145, v[184:187], s[2:3]
	s_and_b64 vcc, exec, s[0:1]
	s_cbranch_vccnz .LBB0_864
